# attention main loop: K-fragment LDS reads prefetched 3 pairs deep (uses v234-249, dead in loop)
# baseline (speedup 1.0000x reference)
; __device__ __forceinline__ void finishSM(f32x16& p0, f32x16& p1, float alpha, float& l_reg, bf16x8& pa0, bf16x8& pa1, bf16x8& pa2, bf16x8& pa3) {
;     for (int r = 0; r < 16; ++r) p1[r] = __builtin_amdgcn_exp2f(p1[r]);
;     float ps = 0; for (int r = 0; r < 16; ++r) ps += p0[r]; for (int r = 0; r < 16; ++r) ps += p1[r];
;     { auto rr = __builtin_amdgcn_permlane32_swap(__float_as_uint(ps), __float_as_uint(ps), false, false);
;       ps = __uint_as_float(rr[0]) + __uint_as_float(rr[1]); }
;     l_reg = l_reg * alpha + ps;
;     ...
;     PK4(p0, 0, pa0); PK4(p0, 8, pa1); PK4(p1, 0, pa2); PK4(p1, 8, pa3);
; template <int KB>
; __device__ __forceinline__ void qkt(f32x16& p0, f32x16& p1, const char* K_lds, int r32, int hi, const bf16x8* qr) {
;     p0 = f32x16{}; p1 = f32x16{};
;     const char* kb[4];
; #pragma unroll
;     for (int dd = 0; dd < 4; ++dd) kb[dd] = K_lds + KB * SHM_K + KSWZ(r32, (dd * 16 + hi * 8) * 2);
; #pragma unroll
;     for (int d0 = 0; d0 < 8; ++d0) { const char* a = kb[d0 & 3] + (d0 >> 2) * 128;
;         bf16x8 b0 = *reinterpret_cast<const bf16x8*>(a);
;         bf16x8 b1 = *reinterpret_cast<const bf16x8*>(a + 32 * 256);
;         p0 = __builtin_amdgcn_mfma_f32_32x32x16_bf16(b0, qr[d0], p0, 0, 0, 0);
;         p1 = __builtin_amdgcn_mfma_f32_32x32x16_bf16(b1, qr[d0], p1, 0, 0, 0); }
.LBB0_89:
	ds_read_b128 v[66:69], v169 offset:49152
	ds_read_b128 v[70:73], v169 offset:57344
	ds_read_b128 v[100:103], v193 offset:49152
	s_waitcnt vmcnt(2)
	ds_read_b128 v[136:139], v193 offset:57344
	ds_read_b128 v[234:237], v194 offset:49152
	ds_read_b128 v[238:241], v194 offset:57344
	ds_read_b128 v[242:245], v195 offset:49152
	ds_read_b128 v[246:249], v195 offset:57344
	v_add_f32_e32 v148, 0, v231
	v_add_f32_e32 v148, v233, v148
	s_waitcnt lgkmcnt(7)
	v_mfma_f32_32x32x16_bf16 v[82:97], v[66:69], v[132:135], 0
	v_add_f32_e32 v148, v229, v148
	v_add_f32_e32 v148, v232, v148
	v_add_f32_e32 v148, v228, v148
	v_add_f32_e32 v148, v230, v148
	v_add_f32_e32 v148, v226, v148
	v_add_f32_e32 v148, v227, v148
	v_add_f32_e32 v148, v223, v148
	s_waitcnt lgkmcnt(6)
	v_mfma_f32_32x32x16_bf16 v[66:81], v[70:73], v[132:135], 0
	v_add_f32_e32 v148, v225, v148
	v_add_f32_e32 v148, v209, v148
	v_add_f32_e32 v148, v224, v148
	v_add_f32_e32 v148, v206, v148
	v_add_f32_e32 v148, v208, v148
	v_add_f32_e32 v148, v205, v148
	v_add_f32_e32 v148, v207, v148
	s_waitcnt lgkmcnt(5)
	v_mfma_f32_32x32x16_bf16 v[82:97], v[100:103], v[128:131], v[82:97]
	s_waitcnt vmcnt(1)
	v_exp_f32_e32 v140, v152
	v_exp_f32_e32 v141, v153
	v_exp_f32_e32 v142, v180
	v_exp_f32_e32 v143, v181
	s_waitcnt vmcnt(0)
	v_exp_f32_e32 v144, v160
	v_exp_f32_e32 v145, v161
	v_exp_f32_e32 v146, v154
	s_waitcnt lgkmcnt(4)
	v_mfma_f32_32x32x16_bf16 v[66:81], v[136:139], v[128:131], v[66:81]
	ds_read_b128 v[100:103], v169 offset:49280
	ds_read_b128 v[136:139], v169 offset:57472
	v_exp_f32_e32 v147, v155
	s_waitcnt lgkmcnt(5)
	v_mfma_f32_32x32x16_bf16 v[82:97], v[234:237], v[124:127], v[82:97]
	s_waitcnt lgkmcnt(4)
	v_mfma_f32_32x32x16_bf16 v[66:81], v[238:241], v[124:127], v[66:81]
	ds_read_b128 v[234:237], v193 offset:49280
	ds_read_b128 v[238:241], v193 offset:57472
	s_waitcnt lgkmcnt(5)
	v_mfma_f32_32x32x16_bf16 v[82:97], v[242:245], v[120:123], v[82:97]
	s_waitcnt lgkmcnt(4)
	v_mfma_f32_32x32x16_bf16 v[66:81], v[246:249], v[120:123], v[66:81]
	ds_read_b128 v[242:245], v194 offset:49280
	ds_read_b128 v[246:249], v194 offset:57472
	s_waitcnt lgkmcnt(5)
	v_mfma_f32_32x32x16_bf16 v[82:97], v[100:103], v[116:119], v[82:97]
	s_waitcnt lgkmcnt(4)
	v_mfma_f32_32x32x16_bf16 v[66:81], v[136:139], v[116:119], v[66:81]
	ds_read_b128 v[100:103], v195 offset:49280
	ds_read_b128 v[136:139], v195 offset:57472
	s_waitcnt lgkmcnt(5)
	v_mfma_f32_32x32x16_bf16 v[82:97], v[234:237], v[112:115], v[82:97]
	s_waitcnt lgkmcnt(4)
	v_mfma_f32_32x32x16_bf16 v[66:81], v[238:241], v[112:115], v[66:81]
	s_waitcnt lgkmcnt(3)
	v_mfma_f32_32x32x16_bf16 v[82:97], v[242:245], v[108:111], v[82:97]
	s_waitcnt lgkmcnt(2)
	v_mfma_f32_32x32x16_bf16 v[66:81], v[246:249], v[108:111], v[66:81]
	s_waitcnt lgkmcnt(1)
	v_mfma_f32_32x32x16_bf16 v[82:97], v[100:103], v[104:107], v[82:97]
	v_exp_f32_e32 v100, v178
	v_exp_f32_e32 v101, v179
	v_exp_f32_e32 v102, v162
	v_exp_f32_e32 v103, v163
	v_add_f32_e32 v148, v100, v148
	v_add_f32_e32 v148, v101, v148
	v_add_f32_e32 v148, v102, v148
	s_waitcnt lgkmcnt(0)
	v_mfma_f32_32x32x16_bf16 v[66:81], v[136:139], v[104:107], v[66:81]
	v_exp_f32_e32 v136, v158
	v_exp_f32_e32 v137, v159
	v_exp_f32_e32 v138, v156
	v_exp_f32_e32 v139, v157
	v_add_f32_e32 v148, v103, v148
	v_add_f32_e32 v148, v136, v148
	v_add_f32_e32 v148, v137, v148
	v_add_f32_e32 v148, v138, v148
	v_add_f32_e32 v148, v139, v148
	v_add_f32_e32 v148, v140, v148
	v_add_f32_e32 v148, v141, v148
	v_add_f32_e32 v148, v142, v148
	v_add_f32_e32 v148, v143, v148
	v_add_f32_e32 v148, v144, v148
	v_add_f32_e32 v148, v145, v148
	v_add_f32_e32 v148, v146, v148
	v_add_f32_e32 v199, v147, v148
	v_mov_b32_e32 v200, v199
	s_nop 1
	v_permlane32_swap_b32_e32 v199, v200
	v_cvt_pk_bf16_f32 v148, v231, v233
	v_cvt_pk_bf16_f32 v149, v229, v232
	v_cvt_pk_bf16_f32 v150, v228, v230
	v_cvt_pk_bf16_f32 v151, v226, v227
	v_cvt_pk_bf16_f32 v152, v223, v225
	v_cvt_pk_bf16_f32 v153, v209, v224
	v_cvt_pk_bf16_f32 v154, v206, v208
	v_cvt_pk_bf16_f32 v155, v205, v207
	v_cvt_pk_bf16_f32 v156, v100, v101
	v_cvt_pk_bf16_f32 v157, v102, v103
	v_cvt_pk_bf16_f32 v158, v136, v137
	v_cvt_pk_bf16_f32 v159, v138, v139
	v_cvt_pk_bf16_f32 v160, v140, v141
	v_cvt_pk_bf16_f32 v161, v142, v143
	v_cvt_pk_bf16_f32 v162, v144, v145
	v_cvt_pk_bf16_f32 v163, v146, v147
	s_nop 0
	v_permlane32_swap_b32_e32 v148, v150
	v_permlane32_swap_b32_e32 v149, v151
	v_permlane32_swap_b32_e32 v152, v154
	v_permlane32_swap_b32_e32 v153, v155
	v_permlane32_swap_b32_e32 v156, v158
	v_permlane32_swap_b32_e32 v157, v159
	v_permlane32_swap_b32_e32 v160, v162
	v_permlane32_swap_b32_e32 v161, v163
	v_add_u32_e32 v178, s7, v166
	v_add_u32_e32 v100, 1, v178
	v_add_u32_e32 v102, 33, v178
	v_ashrrev_i32_e32 v101, 31, v100
	v_ashrrev_i32_e32 v103, 31, v102
	v_lshlrev_b64 v[140:141], 8, v[100:101]
	v_lshlrev_b64 v[142:143], 8, v[102:103]
	v_lshl_add_u64 v[100:101], v[170:171], 0, v[140:141]
	v_lshl_add_u64 v[136:137], v[170:171], 0, v[142:143]
	v_lshl_add_u64 v[140:141], v[176:177], 0, v[140:141]
	v_lshl_add_u64 v[144:145], v[176:177], 0, v[142:143]
	global_load_dwordx4 v[100:103], v[100:101], off
	s_nop 0
	global_load_dwordx4 v[136:139], v[136:137], off
	s_nop 0
	global_load_dwordx4 v[140:143], v[140:141], off
	s_nop 0
	global_load_dwordx4 v[144:147], v[144:145], off
	ds_read_b64_tr_b16 v[172:173], v185 offset:0
	ds_read_b64_tr_b16 v[174:175], v185 offset:0x800
	ds_read_b64_tr_b16 v[202:203], v185 offset:0x1000
	ds_read_b64_tr_b16 v[204:205], v185 offset:0x1800
	ds_read_b64_tr_b16 v[206:207], v185 offset:0x2000
	ds_read_b64_tr_b16 v[208:209], v185 offset:0x2800
	ds_read_b64_tr_b16 v[224:225], v185 offset:0x3000
	ds_read_b64_tr_b16 v[226:227], v185 offset:0x3800
	s_waitcnt lgkmcnt(0)
; __device__ __forceinline__ void mask_tile(f32x16& p0, f32x16& p1, int dq, unsigned W) {
;     const float NEG = -__builtin_inff();
; #pragma unroll
;     for (int r = 0; r < 16; ++r) {
;         const int c = (r & 3) + 8 * (r >> 2);
;         if ((unsigned)(dq - c) >= W) p0[r] = NEG;
;         if ((unsigned)(dq - c - 32) >= W) p1[r] = NEG;
;     }
; }
; template <int VB>
; __device__ __forceinline__ void pv_tile(f32x16* o, int vb0, bf16x8 pa0, bf16x8 pa1, bf16x8 pa2, bf16x8 pa3) {
;     ...
;     PV_D0(0); PV_D0(1); PV_D0(2); PV_D0(3);
;     ...
; }
	s_nop 0
	v_mfma_f32_32x32x16_bf16 v[50:65], v[148:151], v[172:175], v[50:65]
	ds_read_b64_tr_b16 v[172:173], v185 offset:0x200
	ds_read_b64_tr_b16 v[174:175], v185 offset:0xa00
	v_mfma_f32_32x32x16_bf16 v[50:65], v[152:155], v[202:205], v[50:65]
	ds_read_b64_tr_b16 v[202:203], v185 offset:0x1200
	ds_read_b64_tr_b16 v[204:205], v185 offset:0x1a00
	v_mfma_f32_32x32x16_bf16 v[50:65], v[156:159], v[206:209], v[50:65]
	ds_read_b64_tr_b16 v[206:207], v185 offset:0x2200
	ds_read_b64_tr_b16 v[208:209], v185 offset:0x2a00
	v_mfma_f32_32x32x16_bf16 v[50:65], v[160:163], v[224:227], v[50:65]
	ds_read_b64_tr_b16 v[224:225], v185 offset:0x3200
	ds_read_b64_tr_b16 v[226:227], v185 offset:0x3a00
	s_waitcnt lgkmcnt(0)
	v_mfma_f32_32x32x16_bf16 v[34:49], v[148:151], v[172:175], v[34:49]
	ds_read_b64_tr_b16 v[172:173], v185 offset:0x400
	ds_read_b64_tr_b16 v[174:175], v185 offset:0xc00
	v_mfma_f32_32x32x16_bf16 v[34:49], v[152:155], v[202:205], v[34:49]
	ds_read_b64_tr_b16 v[202:203], v185 offset:0x1400
	ds_read_b64_tr_b16 v[204:205], v185 offset:0x1c00
	v_mfma_f32_32x32x16_bf16 v[34:49], v[156:159], v[206:209], v[34:49]
	ds_read_b64_tr_b16 v[206:207], v185 offset:0x2400
	ds_read_b64_tr_b16 v[208:209], v185 offset:0x2c00
	v_mfma_f32_32x32x16_bf16 v[34:49], v[160:163], v[224:227], v[34:49]
	ds_read_b64_tr_b16 v[224:225], v185 offset:0x3400
	ds_read_b64_tr_b16 v[226:227], v185 offset:0x3c00
	s_waitcnt lgkmcnt(0)
	v_mfma_f32_32x32x16_bf16 v[18:33], v[148:151], v[172:175], v[18:33]
	ds_read_b64_tr_b16 v[172:173], v185 offset:0x600
	ds_read_b64_tr_b16 v[174:175], v185 offset:0xe00
	v_mfma_f32_32x32x16_bf16 v[18:33], v[152:155], v[202:205], v[18:33]
	ds_read_b64_tr_b16 v[202:203], v185 offset:0x1600
	ds_read_b64_tr_b16 v[204:205], v185 offset:0x1e00
	v_mfma_f32_32x32x16_bf16 v[18:33], v[156:159], v[206:209], v[18:33]
	ds_read_b64_tr_b16 v[206:207], v185 offset:0x2600
	ds_read_b64_tr_b16 v[208:209], v185 offset:0x2e00
	v_mfma_f32_32x32x16_bf16 v[18:33], v[160:163], v[224:227], v[18:33]
	ds_read_b64_tr_b16 v[224:225], v185 offset:0x3600
	ds_read_b64_tr_b16 v[226:227], v185 offset:0x3e00
	s_waitcnt lgkmcnt(0)
	v_mfma_f32_32x32x16_bf16 v[2:17], v[148:151], v[172:175], v[2:17]
	s_cmp_le_i32 s7, s6
	v_mfma_f32_32x32x16_bf16 v[2:17], v[152:155], v[202:205], v[2:17]
	v_mfma_f32_32x32x16_bf16 v[2:17], v[156:159], v[206:209], v[2:17]
	v_mfma_f32_32x32x16_bf16 v[2:17], v[160:163], v[224:227], v[2:17]
	s_cbranch_scc1 .LBB0_91
	v_add_u32_e32 v148, 0x4000007b, v197
	v_cmp_gt_u32_e32 vcc, 2.0, v148
	v_add_u32_e32 v148, 0x5b, v197
	s_nop 0
	v_cndmask_b32_e32 v82, v220, v82, vcc
	v_cmp_lt_u32_e32 vcc, s33, v148
	v_add_u32_e32 v148, 0x7a, v197
	s_nop 0
	v_cndmask_b32_e32 v66, v220, v66, vcc
	v_cmp_lt_u32_e32 vcc, s33, v148
	v_add_u32_e32 v148, 0x5a, v197
	s_nop 0
	v_cndmask_b32_e32 v83, v220, v83, vcc
	v_cmp_lt_u32_e32 vcc, s33, v148
	v_add_u32_e32 v148, 0x79, v197
	s_nop 0
	v_cndmask_b32_e32 v67, v220, v67, vcc
	v_cmp_lt_u32_e32 vcc, s33, v148
	v_add_u32_e32 v148, 0x59, v197
	s_nop 0
	v_cndmask_b32_e32 v84, v220, v84, vcc
	v_cmp_lt_u32_e32 vcc, s33, v148
	v_add_u32_e32 v148, 0x78, v197
	s_nop 0
	v_cndmask_b32_e32 v68, v220, v68, vcc
	v_cmp_lt_u32_e32 vcc, s33, v148
	v_add_u32_e32 v148, 0x58, v197
	s_nop 0
	v_cndmask_b32_e32 v85, v220, v85, vcc
	v_cmp_lt_u32_e32 vcc, s33, v148
	v_add_u32_e32 v148, 0x73, v197
	s_nop 0
	v_cndmask_b32_e32 v69, v220, v69, vcc
	v_cmp_lt_u32_e32 vcc, s33, v148
	v_add_u32_e32 v148, 0x53, v197
	s_nop 0
	v_cndmask_b32_e32 v86, v220, v86, vcc
	v_cmp_lt_u32_e32 vcc, s33, v148
	v_add_u32_e32 v148, 0x72, v197
	s_nop 0
	v_cndmask_b32_e32 v70, v220, v70, vcc
	v_cmp_lt_u32_e32 vcc, s33, v148
	v_add_u32_e32 v148, 0x52, v197
	s_nop 0
	v_cndmask_b32_e32 v87, v220, v87, vcc
	v_cmp_lt_u32_e32 vcc, s33, v148
	v_add_u32_e32 v148, 0x71, v197
	s_nop 0
	v_cndmask_b32_e32 v71, v220, v71, vcc
	v_cmp_lt_u32_e32 vcc, s33, v148
	v_add_u32_e32 v148, 0x51, v197
	s_nop 0
	v_cndmask_b32_e32 v88, v220, v88, vcc
	v_cmp_lt_u32_e32 vcc, s33, v148
	v_add_u32_e32 v148, 0x70, v197
	s_nop 0
	v_cndmask_b32_e32 v72, v220, v72, vcc
	v_cmp_lt_u32_e32 vcc, s33, v148
	v_add_u32_e32 v148, 0x50, v197
	s_nop 0
	v_cndmask_b32_e32 v89, v220, v89, vcc
	v_cmp_lt_u32_e32 vcc, s33, v148
	v_add_u32_e32 v148, 0x6b, v197
	s_nop 0
	v_cndmask_b32_e32 v73, v220, v73, vcc
	v_cmp_lt_u32_e32 vcc, s33, v148
	v_add_u32_e32 v148, 0x4b, v197
	s_nop 0
	v_cndmask_b32_e32 v90, v220, v90, vcc
	v_cmp_lt_u32_e32 vcc, s33, v148
	v_add_u32_e32 v148, 0x6a, v197
	s_nop 0
	v_cndmask_b32_e32 v74, v220, v74, vcc
	v_cmp_lt_u32_e32 vcc, s33, v148
	v_add_u32_e32 v148, 0x4a, v197
	s_nop 0
	v_cndmask_b32_e32 v91, v220, v91, vcc
	v_cmp_lt_u32_e32 vcc, s33, v148
	v_add_u32_e32 v148, 0x69, v197
	s_nop 0
	v_cndmask_b32_e32 v75, v220, v75, vcc
	v_cmp_lt_u32_e32 vcc, s33, v148
	v_add_u32_e32 v148, 0x49, v197
	s_nop 0
	v_cndmask_b32_e32 v92, v220, v92, vcc
	v_cmp_lt_u32_e32 vcc, s33, v148
	v_add_u32_e32 v148, 0x68, v197
	s_nop 0
	v_cndmask_b32_e32 v76, v220, v76, vcc
	v_cmp_lt_u32_e32 vcc, s33, v148
	v_add_u32_e32 v148, 0x48, v197
	s_nop 0
	v_cndmask_b32_e32 v93, v220, v93, vcc
	v_cmp_lt_u32_e32 vcc, s33, v148
	v_add_u32_e32 v148, 0x63, v197
	s_nop 0
	v_cndmask_b32_e32 v77, v220, v77, vcc
	v_cmp_lt_u32_e32 vcc, s33, v148
	v_add_u32_e32 v148, 0x43, v197
	s_nop 0
	v_cndmask_b32_e32 v94, v220, v94, vcc
	v_cmp_lt_u32_e32 vcc, s33, v148
	v_add_u32_e32 v148, 0x62, v197
	s_nop 0
	v_cndmask_b32_e32 v78, v220, v78, vcc
	v_cmp_lt_u32_e32 vcc, s33, v148
	v_add_u32_e32 v148, 0x42, v197
	s_nop 0
	v_cndmask_b32_e32 v95, v220, v95, vcc
	v_cmp_lt_u32_e32 vcc, s33, v148
	v_add_u32_e32 v148, 0x61, v197
	s_nop 0
	v_cndmask_b32_e32 v79, v220, v79, vcc
	v_cmp_lt_u32_e32 vcc, s33, v148
	v_add_u32_e32 v148, 0x41, v197
	s_nop 0
	v_cndmask_b32_e32 v96, v220, v96, vcc
	v_cmp_lt_u32_e32 vcc, s33, v148
	v_add_u32_e32 v148, 0x60, v197
	s_nop 0
	v_cndmask_b32_e32 v80, v220, v80, vcc
	v_cmp_lt_u32_e32 vcc, s33, v148
	v_add_u32_e32 v148, 64, v197
	s_nop 0
	v_cndmask_b32_e32 v97, v220, v97, vcc
	v_cmp_lt_u32_e32 vcc, s33, v148
	s_nop 1
	v_cndmask_b32_e32 v81, v220, v81, vcc

; __device__ __forceinline__ void partialSM(f32x16& p0, f32x16& p1, float& m_reg, float& mn, float& alpha, bool rs) {
;     ...
;     if (__builtin_expect(__all((pmax - m_reg) * SCALE <= THR), 1)) { mn = m_reg; alpha = 1.f; }
;     else { mn = fmaxf(m_reg, pmax); alpha = __builtin_amdgcn_exp2f((m_reg - mn) * C2); m_reg = mn; }
;     const float mnL = rs ? -mn * C2 : -__builtin_inff();
;     for (int r = 0; r < 16; ++r) p0[r] = fmaf(p0[r], C2, mnL); for (int r = 0; r < 16; ++r) p1[r] = fmaf(p1[r], C2, mnL);
;     for (int r = 0; r < 16; ++r) p0[r] = __builtin_amdgcn_exp2f(p0[r]);
.LBB0_95:
	v_cndmask_b32_e64 v179, v148, v198, s[42:43]
	v_mul_f32_e32 v148, 0xbe0293ee, v179
	v_cndmask_b32_e64 v180, v220, v148, s[40:41]
	v_fmamk_f32 v82, v82, 0x3e0293ee, v180
	v_fmamk_f32 v83, v83, 0x3e0293ee, v180
	v_fmamk_f32 v84, v84, 0x3e0293ee, v180
	v_fmamk_f32 v85, v85, 0x3e0293ee, v180
	v_fmamk_f32 v86, v86, 0x3e0293ee, v180
	v_fmamk_f32 v87, v87, 0x3e0293ee, v180
	v_fmamk_f32 v88, v88, 0x3e0293ee, v180
	v_fmamk_f32 v89, v89, 0x3e0293ee, v180
	v_fmamk_f32 v90, v90, 0x3e0293ee, v180
	v_fmamk_f32 v91, v91, 0x3e0293ee, v180
	v_fmamk_f32 v92, v92, 0x3e0293ee, v180
	v_fmamk_f32 v93, v93, 0x3e0293ee, v180
	v_fmamk_f32 v94, v94, 0x3e0293ee, v180
	v_fmamk_f32 v95, v95, 0x3e0293ee, v180
	v_fmamk_f32 v96, v96, 0x3e0293ee, v180
	v_fmamk_f32 v97, v97, 0x3e0293ee, v180
	v_exp_f32_e32 v148, v82
	v_exp_f32_e32 v163, v83
	v_exp_f32_e32 v149, v84
	v_exp_f32_e32 v162, v85
	v_exp_f32_e32 v150, v86
	v_exp_f32_e32 v161, v87
	v_exp_f32_e32 v151, v88
	v_exp_f32_e32 v160, v89
	v_exp_f32_e32 v152, v90
	v_exp_f32_e32 v159, v91
	v_exp_f32_e32 v153, v92
	v_exp_f32_e32 v158, v93
	v_exp_f32_e32 v154, v94
	v_exp_f32_e32 v157, v95
	v_exp_f32_e32 v155, v96
	v_exp_f32_e32 v156, v97
	v_fmamk_f32 v203, v73, 0x3e0293ee, v180
	v_fmamk_f32 v204, v74, 0x3e0293ee, v180
	v_fmamk_f32 v208, v66, 0x3e0293ee, v180
	v_fmamk_f32 v209, v67, 0x3e0293ee, v180
	v_fmamk_f32 v223, v68, 0x3e0293ee, v180
	v_fmamk_f32 v224, v69, 0x3e0293ee, v180
	v_fmamk_f32 v225, v70, 0x3e0293ee, v180
	v_fmamk_f32 v198, v71, 0x3e0293ee, v180
	v_fmamk_f32 v201, v72, 0x3e0293ee, v180
	v_fmamk_f32 v205, v75, 0x3e0293ee, v180
	v_fmamk_f32 v206, v76, 0x3e0293ee, v180
	v_fmamk_f32 v207, v77, 0x3e0293ee, v180
	v_fmamk_f32 v181, v78, 0x3e0293ee, v180
	v_fmamk_f32 v226, v79, 0x3e0293ee, v180
	v_fmamk_f32 v227, v80, 0x3e0293ee, v180
	v_fmac_f32_e32 v180, 0x3e0293ee, v81
	s_waitcnt lgkmcnt(0)
	s_barrier
; __device__ __forceinline__ void finishSM(f32x16& p0, f32x16& p1, float alpha, float& l_reg, bf16x8& pa0, bf16x8& pa1, bf16x8& pa2, bf16x8& pa3) {
;     for (int r = 0; r < 16; ++r) p1[r] = __builtin_amdgcn_exp2f(p1[r]);
;     float ps = 0; for (int r = 0; r < 16; ++r) ps += p0[r]; for (int r = 0; r < 16; ++r) ps += p1[r];
;     { auto rr = __builtin_amdgcn_permlane32_swap(__float_as_uint(ps), __float_as_uint(ps), false, false);
;       ps = __uint_as_float(rr[0]) + __uint_as_float(rr[1]); }
;     l_reg = l_reg * alpha + ps;
;     ...
;     PK4(p0, 0, pa0); PK4(p0, 8, pa1); PK4(p1, 0, pa2); PK4(p1, 8, pa3);
; template <int KB>
; __device__ __forceinline__ void qkt(f32x16& p0, f32x16& p1, const char* K_lds, int r32, int hi, const bf16x8* qr) {
;     p0 = f32x16{}; p1 = f32x16{};
;     const char* kb[4];
; #pragma unroll
;     for (int dd = 0; dd < 4; ++dd) kb[dd] = K_lds + KB * SHM_K + KSWZ(r32, (dd * 16 + hi * 8) * 2);
; #pragma unroll
;     for (int d0 = 0; d0 < 8; ++d0) { const char* a = kb[d0 & 3] + (d0 >> 2) * 128;
;         bf16x8 b0 = *reinterpret_cast<const bf16x8*>(a);
;         bf16x8 b1 = *reinterpret_cast<const bf16x8*>(a + 32 * 256);
;         p0 = __builtin_amdgcn_mfma_f32_32x32x16_bf16(b0, qr[d0], p0, 0, 0, 0);
;         p1 = __builtin_amdgcn_mfma_f32_32x32x16_bf16(b1, qr[d0], p1, 0, 0, 0); }
; }
	ds_read_b128 v[66:69], v169 offset:32768
	ds_read_b128 v[70:73], v169 offset:40960
	ds_read_b128 v[172:175], v193 offset:32768
	ds_read_b128 v[228:231], v193 offset:40960
	ds_read_b128 v[234:237], v194 offset:32768
	ds_read_b128 v[238:241], v194 offset:40960
	ds_read_b128 v[242:245], v195 offset:32768
	ds_read_b128 v[246:249], v195 offset:40960
	v_exp_f32_e32 v198, v198
	v_exp_f32_e32 v201, v201
	s_waitcnt lgkmcnt(7)
	v_mfma_f32_32x32x16_bf16 v[82:97], v[66:69], v[132:135], 0
	v_exp_f32_e32 v214, v204
	v_exp_f32_e32 v205, v205
	v_exp_f32_e32 v206, v206
	v_exp_f32_e32 v207, v207
	v_exp_f32_e32 v181, v181
	v_exp_f32_e32 v215, v226
	v_exp_f32_e32 v216, v227
	s_waitcnt lgkmcnt(6)
	v_mfma_f32_32x32x16_bf16 v[66:81], v[70:73], v[132:135], 0
	v_exp_f32_e32 v180, v180
	s_waitcnt lgkmcnt(5)
	v_mfma_f32_32x32x16_bf16 v[82:97], v[172:175], v[128:131], v[82:97]
	s_waitcnt lgkmcnt(4)
	v_mfma_f32_32x32x16_bf16 v[66:81], v[228:231], v[128:131], v[66:81]
	ds_read_b128 v[172:175], v169 offset:32896
	ds_read_b128 v[228:231], v169 offset:41088
	s_waitcnt lgkmcnt(5)
	v_mfma_f32_32x32x16_bf16 v[82:97], v[234:237], v[124:127], v[82:97]
	s_waitcnt lgkmcnt(4)
	v_mfma_f32_32x32x16_bf16 v[66:81], v[238:241], v[124:127], v[66:81]
	ds_read_b128 v[234:237], v193 offset:32896
	ds_read_b128 v[238:241], v193 offset:41088
	s_waitcnt lgkmcnt(5)
	v_mfma_f32_32x32x16_bf16 v[82:97], v[242:245], v[120:123], v[82:97]
	s_waitcnt lgkmcnt(4)
	v_mfma_f32_32x32x16_bf16 v[66:81], v[246:249], v[120:123], v[66:81]
	ds_read_b128 v[242:245], v194 offset:32896
	ds_read_b128 v[246:249], v194 offset:41088
	s_waitcnt lgkmcnt(5)
	v_mfma_f32_32x32x16_bf16 v[82:97], v[172:175], v[116:119], v[82:97]
	s_waitcnt lgkmcnt(4)
	v_mfma_f32_32x32x16_bf16 v[66:81], v[228:231], v[116:119], v[66:81]
	ds_read_b128 v[172:175], v195 offset:32896
	ds_read_b128 v[228:231], v195 offset:41088
	s_waitcnt lgkmcnt(5)
	v_mfma_f32_32x32x16_bf16 v[82:97], v[234:237], v[112:115], v[82:97]
	s_waitcnt lgkmcnt(4)
	v_mfma_f32_32x32x16_bf16 v[66:81], v[238:241], v[112:115], v[66:81]
	s_waitcnt lgkmcnt(3)
	v_mfma_f32_32x32x16_bf16 v[82:97], v[242:245], v[108:111], v[82:97]
	s_waitcnt lgkmcnt(2)
	v_mfma_f32_32x32x16_bf16 v[66:81], v[246:249], v[108:111], v[66:81]
	s_waitcnt lgkmcnt(1)
	v_mfma_f32_32x32x16_bf16 v[82:97], v[172:175], v[104:107], v[82:97]
	v_exp_f32_e32 v173, v209
	v_exp_f32_e32 v209, v203
	v_add_f32_e32 v203, 0, v148
	v_add_f32_e32 v203, v163, v203
	v_add_f32_e32 v203, v149, v203
	v_add_f32_e32 v203, v162, v203
	v_add_f32_e32 v203, v150, v203
	v_add_f32_e32 v203, v161, v203
	v_add_f32_e32 v203, v151, v203
	v_add_f32_e32 v203, v160, v203
	v_add_f32_e32 v203, v152, v203
	v_add_f32_e32 v203, v159, v203
	v_add_f32_e32 v203, v153, v203
	v_add_f32_e32 v203, v158, v203
	v_exp_f32_e32 v172, v208
	v_add_f32_e32 v203, v154, v203
	v_add_f32_e32 v203, v157, v203
	v_exp_f32_e32 v174, v223
	v_add_f32_e32 v203, v155, v203
	v_exp_f32_e32 v175, v224
	v_add_f32_e32 v203, v156, v203
	v_exp_f32_e32 v208, v225
	v_add_f32_e32 v203, v172, v203
	v_add_f32_e32 v203, v173, v203
	v_add_f32_e32 v203, v174, v203
	v_add_f32_e32 v203, v175, v203
	v_add_f32_e32 v203, v208, v203
	v_add_f32_e32 v203, v198, v203
	v_add_f32_e32 v203, v201, v203
	v_add_f32_e32 v203, v209, v203
	v_add_f32_e32 v203, v214, v203
	v_add_f32_e32 v203, v205, v203
	s_waitcnt lgkmcnt(0)
	v_mfma_f32_32x32x16_bf16 v[66:81], v[228:231], v[104:107], v[66:81]
	v_add_f32_e32 v203, v206, v203
	v_add_f32_e32 v203, v207, v203
	v_add_f32_e32 v203, v181, v203
	v_add_f32_e32 v203, v215, v203
	v_add_f32_e32 v203, v216, v203
	v_add_f32_e32 v203, v180, v203
	v_mov_b32_e32 v204, v203
	v_cvt_pk_bf16_f32 v148, v148, v163
	v_cvt_pk_bf16_f32 v149, v149, v162
	v_cvt_pk_bf16_f32 v150, v150, v161
	v_cvt_pk_bf16_f32 v151, v151, v160
	v_cvt_pk_bf16_f32 v152, v152, v159
	v_cvt_pk_bf16_f32 v153, v153, v158
	v_cvt_pk_bf16_f32 v154, v154, v157
	v_cvt_pk_bf16_f32 v155, v155, v156
	v_cvt_pk_bf16_f32 v156, v172, v173
	v_cvt_pk_bf16_f32 v157, v174, v175
	v_cvt_pk_bf16_f32 v158, v208, v198
	v_cvt_pk_bf16_f32 v159, v201, v209
	v_cvt_pk_bf16_f32 v160, v214, v205
	v_cvt_pk_bf16_f32 v161, v206, v207
	v_cvt_pk_bf16_f32 v162, v181, v215
	v_cvt_pk_bf16_f32 v163, v216, v180
	s_nop 1
	v_permlane32_swap_b32_e32 v203, v204
	v_permlane32_swap_b32_e32 v148, v150
	v_permlane32_swap_b32_e32 v149, v151
	v_permlane32_swap_b32_e32 v152, v154
	v_permlane32_swap_b32_e32 v153, v155
	v_permlane32_swap_b32_e32 v156, v158
	v_permlane32_swap_b32_e32 v157, v159
	v_permlane32_swap_b32_e32 v160, v162
	v_permlane32_swap_b32_e32 v161, v163
	s_cmp_lt_u32 s3, s2
	s_cselect_b64 s[22:23], -1, 0
	s_cmp_ge_u32 s3, s2
	s_cbranch_scc1 .LBB0_97
	v_add_u32_e32 v100, 0x41, v178
	v_add_u32_e32 v102, 0x61, v178
	v_ashrrev_i32_e32 v101, 31, v100
	v_ashrrev_i32_e32 v103, 31, v102
	v_lshlrev_b64 v[140:141], 8, v[100:101]
	v_lshlrev_b64 v[142:143], 8, v[102:103]
	v_lshl_add_u64 v[100:101], v[170:171], 0, v[140:141]
	v_lshl_add_u64 v[136:137], v[170:171], 0, v[142:143]
	v_lshl_add_u64 v[140:141], v[176:177], 0, v[140:141]
	v_lshl_add_u64 v[144:145], v[176:177], 0, v[142:143]
	global_load_dwordx4 v[100:103], v[100:101], off
	s_nop 0
	global_load_dwordx4 v[136:139], v[136:137], off
	s_nop 0
	global_load_dwordx4 v[140:143], v[140:141], off
	s_nop 0
	global_load_dwordx4 v[144:147], v[144:145], off
